# sample attention: rope-part sum of squares computed once per token at staging (8-lane DPP reduce of the f32 values, before the prefetch loads reuse the registers) instead of per wave from the bf16 til
# speedup vs baseline: 1.0105x; 1.0029x over previous
.LBB0_1610:
	s_nop 0
	ds_read_b128 v[16:19], v215
	ds_read_b128 v[20:23], v216
	ds_read_b128 v[24:27], v215 offset:64
	ds_read_b128 v[28:31], v216 offset:64
	ds_read_b128 v[190:193], v215 offset:512
	s_add_i32 s43, s42, 1
	s_waitcnt lgkmcnt(5)
	v_add_f32_e32 v246, v250, v249
	v_add_f32_e32 v247, v251, v248
	v_cndmask_b32_e64 v246, v247, v246, s[6:7]
	v_fmamk_f32 v246, v246, 0x3c2aaaab, v209
	v_mul_f32_e32 v249, 0x4f800000, v246
	v_cmp_gt_f32_e32 vcc, s37, v246
	s_waitcnt lgkmcnt(3)
	v_mfma_f32_16x16x32_bf16 v[16:19], v[16:19], v[20:23], 0
	ds_read_b128 v[20:23], v215 offset:128
	ds_read_b128 v[230:233], v216 offset:128
	s_cmp_ge_u32 s43, s39
	s_nop 1
	v_cndmask_b32_e32 v246, v246, v249, vcc
	v_sqrt_f32_e32 v249, v246
	s_nop 0
	v_add_u32_e32 v250, -1, v249
	v_fma_f32 v252, -v250, v249, v246
	v_add_u32_e32 v251, 1, v249
	s_waitcnt lgkmcnt(3)
	v_mfma_f32_16x16x32_bf16 v[16:19], v[24:27], v[28:31], v[16:19]
	ds_read_b128 v[24:27], v215 offset:192
	ds_read_b128 v[28:31], v216 offset:192
	v_cmp_ge_f32_e64 s[10:11], 0, v252
	s_nop 1
	v_cndmask_b32_e64 v250, v249, v250, s[10:11]
	v_fma_f32 v249, -v251, v249, v246
	v_cmp_lt_f32_e64 s[10:11], 0, v249
	s_nop 1
	v_cndmask_b32_e64 v249, v250, v251, s[10:11]
	s_waitcnt lgkmcnt(2)
	v_mfma_f32_16x16x32_bf16 v[16:19], v[20:23], v[230:233], v[16:19]
	ds_read_b128 v[20:23], v215 offset:256
	ds_read_b128 v[230:233], v216 offset:256
	v_mul_f32_e32 v250, 0x37800000, v249
	v_cndmask_b32_e32 v249, v249, v250, vcc
	v_cmp_class_f32_e32 vcc, v246, v210
	s_nop 1
	v_cndmask_b32_e32 v246, v249, v246, vcc
	v_div_scale_f32 v249, s[10:11], v246, v246, 1.0
	v_rcp_f32_e32 v250, v249
	s_waitcnt lgkmcnt(2)
	v_mfma_f32_16x16x32_bf16 v[16:19], v[24:27], v[28:31], v[16:19]
	ds_read_b128 v[24:27], v215 offset:320
	ds_read_b128 v[28:31], v216 offset:320
	s_nop 0
	v_fma_f32 v248, -v249, v250, 1.0
	v_fmac_f32_e32 v250, v248, v250
	v_div_scale_f32 v248, vcc, 1.0, v246, 1.0
	v_mul_f32_e32 v251, v248, v250
	v_fma_f32 v253, -v249, v251, v248
	v_fmac_f32_e32 v251, v253, v250
	s_waitcnt lgkmcnt(2)
	v_mfma_f32_16x16x32_bf16 v[16:19], v[20:23], v[230:233], v[16:19]
	ds_read_b128 v[20:23], v215 offset:384
	ds_read_b128 v[230:233], v216 offset:384
	v_fma_f32 v248, -v249, v251, v248
	s_nop 0
	v_div_fmas_f32 v248, v248, v250, v251
	v_div_fixup_f32 v246, v248, v246, 1.0
	s_waitcnt lgkmcnt(2)
	v_mfma_f32_16x16x32_bf16 v[16:19], v[24:27], v[28:31], v[16:19]
	ds_read_b128 v[24:27], v215 offset:448
	ds_read_b128 v[28:31], v216 offset:448
	ds_read_b128 v[234:237], v216 offset:512
	ds_write_b32 v203, v246
	s_waitcnt lgkmcnt(0)
	s_barrier
	v_mfma_f32_16x16x32_bf16 v[16:19], v[20:23], v[230:233], v[16:19]
	ds_read_b32 v20, v217
	v_mfma_f32_16x16x32_bf16 v[16:19], v[24:27], v[28:31], v[16:19]
	v_mfma_f32_16x16x32_bf16 v[16:19], v[190:193], v[234:237], v[16:19]
	ds_read_b128 v[246:249], v211
	ds_read_b128 v[250:253], v211 offset:16
	ds_read_b128 v[24:27], v211 offset:64
	ds_read_b128 v[28:31], v211 offset:80
	s_waitcnt lgkmcnt(4)
	s_nop 6
	v_fma_f32 v16, v16, v20, -v177
	v_fma_f32 v17, v17, v20, -v177
	v_fma_f32 v18, v18, v20, -v177
	v_fma_f32 v19, v19, v20, -v177
	v_exp_f32_e32 v192, v16
	v_exp_f32_e32 v193, v17
	v_exp_f32_e32 v190, v18
	v_exp_f32_e32 v191, v19
	v_bfe_u32 v16, v192, 16, 1
	v_bfe_u32 v17, v193, 16, 1
	v_bfe_u32 v18, v190, 16, 1
	v_bfe_u32 v19, v191, 16, 1
	v_add3_u32 v16, v192, v16, s38
	v_add3_u32 v17, v193, v17, s38
	v_add3_u32 v18, v190, v18, s38
	v_add3_u32 v19, v191, v19, s38
	ds_write_b16_d16_hi v218, v16
	ds_write_b16_d16_hi v218, v17 offset:144
	ds_write_b16_d16_hi v218, v18 offset:288
	ds_write_b16_d16_hi v218, v19 offset:432
	s_cbranch_scc1 .LBB0_1613
	s_waitcnt lgkmcnt(6)
	v_mfma_scale_f32_32x32x64_f8f6f4 v[230:245], v[32:39], v[246:253], 0, v208, v208 op_sel_hi:[0,0,0]
	v_cvt_pk_bf16_f32 v16, v96, v97
	v_cvt_pk_bf16_f32 v17, v98, v99
	ds_write_b64 v201, v[16:17] offset:37888
	v_cvt_pk_bf16_f32 v18, v100, v101
	v_cvt_pk_bf16_f32 v19, v102, v103
	ds_write_b64 v201, v[18:19] offset:42624
	v_cvt_pk_bf16_f32 v20, v104, v105
	v_cvt_pk_bf16_f32 v21, v106, v107
	ds_write_b64 v201, v[20:21] offset:47360
	v_cvt_pk_bf16_f32 v22, v108, v109
	v_cvt_pk_bf16_f32 v23, v110, v111
	ds_write_b64 v201, v[22:23] offset:52096
	ds_read_b128 v[246:249], v211 offset:128
	ds_read_b128 v[250:253], v211 offset:144
	s_waitcnt lgkmcnt(10)
	v_mfma_scale_f32_32x32x64_f8f6f4 v[230:245], v[40:47], v[24:31], v[230:245], v208, v208 op_sel_hi:[0,0,0]
	v_cvt_pk_bf16_f32 v16, v112, v113
	v_cvt_pk_bf16_f32 v17, v114, v115
	ds_write_b64 v201, v[16:17] offset:56832
	v_cvt_pk_bf16_f32 v18, v116, v117
	v_cvt_pk_bf16_f32 v19, v118, v119
	ds_write_b64 v201, v[18:19] offset:61568
	v_cvt_pk_bf16_f32 v20, v120, v121
	v_cvt_pk_bf16_f32 v21, v122, v123
	ds_write_b64 v204, v[20:21] offset:28416
	v_cvt_pk_bf16_f32 v22, v124, v125
	v_cvt_pk_bf16_f32 v23, v126, v127
	ds_write_b64 v204, v[22:23] offset:33152
	v_mul_f32_e32 v18, v128, v128
	v_fmac_f32_e32 v18, v129, v129
	v_fmac_f32_e32 v18, v130, v130
	v_fmac_f32_e32 v18, v131, v131
	v_cvt_pk_bf16_f32 v16, v128, v129
	v_cvt_pk_bf16_f32 v17, v130, v131
	v_add_f32_dpp v18, v18, v18 quad_perm:[1,0,3,2] row_mask:0xf bank_mask:0xf
	ds_write_b64 v213, v[16:17] offset:38400
	s_nop 0
	v_add_f32_dpp v18, v18, v18 quad_perm:[2,3,0,1] row_mask:0xf bank_mask:0xf
	s_nop 1
	v_add_f32_dpp v18, v18, v18 row_half_mirror row_mask:0xf bank_mask:0xf
	v_mul_f32_e32 v18, 0.5, v18
	ds_write_b32 v202, v18 offset:2048
	ds_read_b128 v[24:27], v211 offset:192
	ds_read_b128 v[28:31], v211 offset:208
	s_waitcnt lgkmcnt(8)
	v_mfma_scale_f32_32x32x64_f8f6f4 v[230:245], v[48:55], v[246:253], v[230:245], v208, v208 op_sel_hi:[0,0,0]
	v_readlane_b32 s0, v227, s41
	s_ashr_i32 s1, s0, 31
	s_lshl_b64 s[0:1], s[0:1], 7
	s_or_b32 s0, s0, 64
	s_lshl_b64 s[2:3], s[0:1], 10
	v_lshl_add_u64 v[16:17], v[182:183], 0, s[2:3]
	v_add_co_u32_e32 v18, vcc, 0x2000, v16
	s_lshl_b64 s[0:1], s[0:1], 7
	s_nop 0
	v_addc_co_u32_e32 v19, vcc, 0, v17, vcc
	global_load_dwordx4 v[96:99], v[16:17], off nt
	global_load_dwordx4 v[100:103], v[18:19], off nt
	v_add_co_u32_e32 v18, vcc, 0x4000, v16
	s_nop 1
	v_addc_co_u32_e32 v19, vcc, 0, v17, vcc
	v_add_co_u32_e32 v20, vcc, 0x6000, v16
	s_nop 1
	v_addc_co_u32_e32 v21, vcc, 0, v17, vcc
	global_load_dwordx4 v[104:107], v[18:19], off nt
	ds_read_b128 v[246:249], v211
	ds_read_b128 v[250:253], v211 offset:16
	s_waitcnt lgkmcnt(2)
	v_mfma_scale_f32_32x32x64_f8f6f4 v[230:245], v[56:63], v[24:31], v[230:245], v208, v208 op_sel_hi:[0,0,0]
	global_load_dwordx4 v[108:111], v[20:21], off nt
	v_add_co_u32_e32 v18, vcc, 0x8000, v16
	s_nop 1
	v_addc_co_u32_e32 v19, vcc, 0, v17, vcc
	v_add_co_u32_e32 v20, vcc, 0xa000, v16
	s_nop 1
	v_addc_co_u32_e32 v21, vcc, 0, v17, vcc
	global_load_dwordx4 v[112:115], v[18:19], off nt
	global_load_dwordx4 v[116:119], v[20:21], off nt
	v_add_co_u32_e32 v18, vcc, 0xc000, v16
	s_nop 1
	v_addc_co_u32_e32 v19, vcc, 0, v17, vcc
	v_add_co_u32_e32 v16, vcc, 0xe000, v16
	s_nop 1
	v_addc_co_u32_e32 v17, vcc, 0, v17, vcc
	global_load_dwordx4 v[120:123], v[18:19], off nt
	global_load_dwordx4 v[124:127], v[16:17], off nt
	v_lshl_add_u64 v[16:17], v[184:185], 0, s[0:1]
	global_load_dwordx4 v[128:131], v[16:17], off nt
	ds_read_b128 v[24:27], v211 offset:64
	ds_read_b128 v[28:31], v211 offset:80
	v_mul_f32_e32 v180, v231, v231
	v_fmac_f32_e32 v180, v230, v230
	v_fmac_f32_e32 v180, v232, v232
	v_fmac_f32_e32 v180, v233, v233
	v_fmac_f32_e32 v180, v234, v234
	v_fmac_f32_e32 v180, v235, v235
	v_fmac_f32_e32 v180, v236, v236
	v_fmac_f32_e32 v180, v237, v237
	v_fmac_f32_e32 v180, v238, v238
	v_fmac_f32_e32 v180, v239, v239
	v_fmac_f32_e32 v180, v240, v240
	v_fmac_f32_e32 v180, v241, v241
	v_fmac_f32_e32 v180, v242, v242
	v_fmac_f32_e32 v180, v243, v243
	v_fmac_f32_e32 v180, v244, v244
	v_fmac_f32_e32 v180, v245, v245
	s_waitcnt lgkmcnt(2)
	v_mfma_scale_f32_32x32x64_f8f6f4 v[230:245], v[64:71], v[246:253], 0, v208, v208 op_sel_hi:[0,0,0]
	ds_read_b128 v[246:249], v211 offset:128
	ds_read_b128 v[250:253], v211 offset:144
	s_waitcnt lgkmcnt(2)
	v_mfma_scale_f32_32x32x64_f8f6f4 v[230:245], v[72:79], v[24:31], v[230:245], v208, v208 op_sel_hi:[0,0,0]
	ds_read_b128 v[24:27], v211 offset:192
	ds_read_b128 v[28:31], v211 offset:208
	s_waitcnt lgkmcnt(2)
	v_mfma_scale_f32_32x32x64_f8f6f4 v[230:245], v[80:87], v[246:253], v[230:245], v208, v208 op_sel_hi:[0,0,0]
	ds_read_b128 v[246:249], v211 offset:8704
	ds_read_b128 v[250:253], v211 offset:8720
	s_waitcnt lgkmcnt(2)
	v_mfma_scale_f32_32x32x64_f8f6f4 v[230:245], v[88:95], v[24:31], v[230:245], v208, v208 op_sel_hi:[0,0,0]
	ds_read_b128 v[24:27], v211 offset:8768
	ds_read_b128 v[28:31], v211 offset:8784
	s_nop 15
	s_nop 1
	v_fmac_f32_e32 v180, v230, v230
	v_fmac_f32_e32 v180, v231, v231
	v_fmac_f32_e32 v180, v232, v232
	v_fmac_f32_e32 v180, v233, v233
	v_fmac_f32_e32 v180, v234, v234
	v_fmac_f32_e32 v180, v235, v235
	v_fmac_f32_e32 v180, v236, v236
	v_fmac_f32_e32 v180, v237, v237
	v_fmac_f32_e32 v180, v238, v238
	v_fmac_f32_e32 v180, v239, v239
	v_fmac_f32_e32 v180, v240, v240
	v_fmac_f32_e32 v180, v241, v241
	v_fmac_f32_e32 v180, v242, v242
	v_fmac_f32_e32 v180, v243, v243
	v_fmac_f32_e32 v180, v244, v244
	v_fmac_f32_e32 v180, v245, v245
	s_waitcnt lgkmcnt(2)
	v_mfma_scale_f32_32x32x64_f8f6f4 v[230:245], v[32:39], v[246:253], 0, v208, v208 op_sel_hi:[0,0,0]
	ds_read_b128 v[246:249], v211 offset:8832
	ds_read_b128 v[250:253], v211 offset:8848
	s_waitcnt lgkmcnt(2)
	v_mfma_scale_f32_32x32x64_f8f6f4 v[230:245], v[40:47], v[24:31], v[230:245], v208, v208 op_sel_hi:[0,0,0]
	ds_read_b128 v[24:27], v211 offset:8896
	ds_read_b128 v[28:31], v211 offset:8912
	s_waitcnt lgkmcnt(2)
	v_mfma_scale_f32_32x32x64_f8f6f4 v[230:245], v[48:55], v[246:253], v[230:245], v208, v208 op_sel_hi:[0,0,0]
	ds_read_b128 v[246:249], v211 offset:8704
	ds_read_b128 v[250:253], v211 offset:8720
	s_waitcnt lgkmcnt(2)
	v_mfma_scale_f32_32x32x64_f8f6f4 v[230:245], v[56:63], v[24:31], v[230:245], v208, v208 op_sel_hi:[0,0,0]
	ds_read_b128 v[24:27], v211 offset:8768
	ds_read_b128 v[28:31], v211 offset:8784
	s_nop 15
	s_nop 1
	v_mul_f32_e32 v229, v231, v231
	v_fmac_f32_e32 v229, v230, v230
	v_fmac_f32_e32 v229, v232, v232
	v_fmac_f32_e32 v229, v233, v233
	v_fmac_f32_e32 v229, v234, v234
	v_fmac_f32_e32 v229, v235, v235
	v_fmac_f32_e32 v229, v236, v236
	v_fmac_f32_e32 v229, v237, v237
	v_fmac_f32_e32 v229, v238, v238
	v_fmac_f32_e32 v229, v239, v239
	v_fmac_f32_e32 v229, v240, v240
	v_fmac_f32_e32 v229, v241, v241
	v_fmac_f32_e32 v229, v242, v242
	v_fmac_f32_e32 v229, v243, v243
	v_fmac_f32_e32 v229, v244, v244
	v_fmac_f32_e32 v229, v245, v245
	s_waitcnt lgkmcnt(2)
	v_mfma_scale_f32_32x32x64_f8f6f4 v[230:245], v[64:71], v[246:253], 0, v208, v208 op_sel_hi:[0,0,0]
	ds_read_b128 v[246:249], v211 offset:8832
	ds_read_b128 v[250:253], v211 offset:8848
	s_waitcnt lgkmcnt(2)
	v_mfma_scale_f32_32x32x64_f8f6f4 v[230:245], v[72:79], v[24:31], v[230:245], v208, v208 op_sel_hi:[0,0,0]
	ds_read_b128 v[24:27], v211 offset:8896
	ds_read_b128 v[28:31], v211 offset:8912
	s_waitcnt lgkmcnt(2)
	v_mfma_scale_f32_32x32x64_f8f6f4 v[230:245], v[80:87], v[246:253], v[230:245], v208, v208 op_sel_hi:[0,0,0]
	s_waitcnt lgkmcnt(0)
	v_mfma_scale_f32_32x32x64_f8f6f4 v[230:245], v[88:95], v[24:31], v[230:245], v208, v208 op_sel_hi:[0,0,0]
	s_waitcnt vmcnt(9)
	v_cvt_pk_fp8_f32 v16, v136, v137
	v_cvt_pk_fp8_f32 v17, v148, v149
	v_cvt_pk_fp8_f32 v18, v160, v161
	v_cvt_pk_fp8_f32 v19, v144, v145
	v_cvt_pk_fp8_f32 v20, v156, v157
	v_cvt_pk_fp8_f32 v21, v140, v141
	v_cvt_pk_fp8_f32 v22, v152, v153
	v_cvt_pk_fp8_f32 v23, v164, v165
	v_cvt_pk_fp8_f32 v16, v138, v139 op_sel:[0,0,1]
	v_cvt_pk_fp8_f32 v17, v150, v151 op_sel:[0,0,1]
	v_cvt_pk_fp8_f32 v18, v162, v163 op_sel:[0,0,1]
	v_cvt_pk_fp8_f32 v19, v146, v147 op_sel:[0,0,1]
	v_cvt_pk_fp8_f32 v20, v158, v159 op_sel:[0,0,1]
	v_cvt_pk_fp8_f32 v21, v142, v143 op_sel:[0,0,1]
	v_cvt_pk_fp8_f32 v22, v154, v155 op_sel:[0,0,1]
	v_cvt_pk_fp8_f32 v23, v166, v167 op_sel:[0,0,1]
	s_nop 1
	ds_write_b32 v228, v16
	ds_write_b32 v228, v17 offset:2176
	ds_write_b32 v228, v18 offset:4352
	ds_write_b32 v228, v19 offset:6528
	ds_write_b32 v228, v20 offset:8704
	ds_write_b32 v228, v21 offset:10880
	ds_write_b32 v228, v22 offset:13056
	ds_write_b32 v228, v23 offset:15232
	v_fmac_f32_e32 v229, v230, v230
	v_fmac_f32_e32 v229, v231, v231
	v_fmac_f32_e32 v229, v232, v232
	v_fmac_f32_e32 v229, v233, v233
	v_fmac_f32_e32 v229, v234, v234
	v_fmac_f32_e32 v229, v235, v235
	v_fmac_f32_e32 v229, v236, v236
	v_fmac_f32_e32 v229, v237, v237
	v_fmac_f32_e32 v229, v238, v238
	v_fmac_f32_e32 v229, v239, v239
	v_fmac_f32_e32 v229, v240, v240
	v_fmac_f32_e32 v229, v241, v241
	v_fmac_f32_e32 v229, v242, v242
	v_fmac_f32_e32 v229, v243, v243
	v_fmac_f32_e32 v229, v244, v244
	v_fmac_f32_e32 v229, v245, v245

.LBB0_1615:
	s_nop 0
	ds_read_b128 v[16:19], v215
	ds_read_b128 v[20:23], v216 offset:37888
	ds_read_b128 v[24:27], v215 offset:64
	ds_read_b128 v[28:31], v216 offset:37952
	ds_read_b128 v[230:233], v215 offset:512
	s_add_i32 s44, s42, 2
	s_waitcnt lgkmcnt(5)
	v_add_f32_e32 v246, v250, v249
	v_add_f32_e32 v247, v251, v248
	v_cndmask_b32_e64 v246, v247, v246, s[6:7]
	v_fmamk_f32 v246, v246, 0x3c2aaaab, v209
	v_mul_f32_e32 v249, 0x4f800000, v246
	v_cmp_gt_f32_e32 vcc, s37, v246
	s_waitcnt lgkmcnt(3)
	v_mfma_f32_16x16x32_bf16 v[16:19], v[16:19], v[20:23], 0
	ds_read_b128 v[20:23], v215 offset:128
	ds_read_b128 v[234:237], v216 offset:38016
	s_cmp_ge_u32 s44, s39
	s_cselect_b64 s[0:1], -1, 0
	s_nop 1
	v_cndmask_b32_e32 v246, v246, v249, vcc
	v_sqrt_f32_e32 v249, v246
	s_nop 0
	v_add_u32_e32 v250, -1, v249
	v_fma_f32 v252, -v250, v249, v246
	v_add_u32_e32 v251, 1, v249
	s_waitcnt lgkmcnt(3)
	v_mfma_f32_16x16x32_bf16 v[16:19], v[24:27], v[28:31], v[16:19]
	ds_read_b128 v[24:27], v215 offset:192
	ds_read_b128 v[28:31], v216 offset:38080
	v_cmp_ge_f32_e64 s[10:11], 0, v252
	s_nop 1
	v_cndmask_b32_e64 v250, v249, v250, s[10:11]
	v_fma_f32 v249, -v251, v249, v246
	v_cmp_lt_f32_e64 s[10:11], 0, v249
	s_nop 1
	v_cndmask_b32_e64 v249, v250, v251, s[10:11]
	s_waitcnt lgkmcnt(2)
	v_mfma_f32_16x16x32_bf16 v[16:19], v[20:23], v[234:237], v[16:19]
	ds_read_b128 v[20:23], v215 offset:256
	ds_read_b128 v[234:237], v216 offset:38144
	v_mul_f32_e32 v250, 0x37800000, v249
	v_cndmask_b32_e32 v249, v249, v250, vcc
	v_cmp_class_f32_e32 vcc, v246, v210
	s_nop 1
	v_cndmask_b32_e32 v246, v249, v246, vcc
	v_div_scale_f32 v249, s[10:11], v246, v246, 1.0
	v_rcp_f32_e32 v250, v249
	s_waitcnt lgkmcnt(2)
	v_mfma_f32_16x16x32_bf16 v[16:19], v[24:27], v[28:31], v[16:19]
	ds_read_b128 v[24:27], v215 offset:320
	ds_read_b128 v[28:31], v216 offset:38208
	s_nop 0
	v_fma_f32 v248, -v249, v250, 1.0
	v_fmac_f32_e32 v250, v248, v250
	v_div_scale_f32 v248, vcc, 1.0, v246, 1.0
	v_mul_f32_e32 v251, v248, v250
	v_fma_f32 v253, -v249, v251, v248
	v_fmac_f32_e32 v251, v253, v250
	s_waitcnt lgkmcnt(2)
	v_mfma_f32_16x16x32_bf16 v[16:19], v[20:23], v[234:237], v[16:19]
	ds_read_b128 v[20:23], v215 offset:384
	ds_read_b128 v[234:237], v216 offset:38272
	v_fma_f32 v248, -v249, v251, v248
	s_nop 0
	v_div_fmas_f32 v248, v248, v250, v251
	v_div_fixup_f32 v246, v248, v246, 1.0
	s_waitcnt lgkmcnt(2)
	v_mfma_f32_16x16x32_bf16 v[16:19], v[24:27], v[28:31], v[16:19]
	ds_read_b128 v[24:27], v215 offset:448
	ds_read_b128 v[28:31], v216 offset:38336
	ds_read_b128 v[238:241], v216 offset:38400
	ds_write_b32 v203, v246
	s_and_b64 vcc, exec, s[0:1]
	s_waitcnt lgkmcnt(0)
	s_barrier
	v_mfma_f32_16x16x32_bf16 v[16:19], v[20:23], v[234:237], v[16:19]
	ds_read_b32 v20, v217
	v_mfma_f32_16x16x32_bf16 v[16:19], v[24:27], v[28:31], v[16:19]
	v_mfma_f32_16x16x32_bf16 v[16:19], v[230:233], v[238:241], v[16:19]
	ds_read_b128 v[246:249], v207
	ds_read_b128 v[250:253], v207 offset:16
	ds_read_b128 v[24:27], v207 offset:64
	ds_read_b128 v[28:31], v207 offset:80
	s_waitcnt lgkmcnt(4)
	s_nop 6
	v_fma_f32 v16, v16, v20, -v177
	v_fma_f32 v17, v17, v20, -v177
	v_fma_f32 v18, v18, v20, -v177
	v_fma_f32 v19, v19, v20, -v177
	v_exp_f32_e32 v16, v16
	v_exp_f32_e32 v17, v17
	v_exp_f32_e32 v18, v18
	v_exp_f32_e32 v19, v19
	v_add_f32_e32 v188, v188, v192
	v_add_f32_e32 v189, v189, v193
	v_add_f32_e32 v186, v186, v190
	v_add_f32_e32 v187, v187, v191
	v_add_f32_e32 v188, v188, v16
	v_add_f32_e32 v189, v189, v17
	v_add_f32_e32 v186, v186, v18
	v_add_f32_e32 v187, v187, v19
	v_bfe_u32 v20, v16, 16, 1
	v_bfe_u32 v21, v17, 16, 1
	v_bfe_u32 v22, v18, 16, 1
	v_bfe_u32 v23, v19, 16, 1
	v_add3_u32 v20, v16, v20, s38
	v_add3_u32 v21, v17, v21, s38
	v_add3_u32 v22, v18, v22, s38
	v_add3_u32 v23, v19, v23, s38
	ds_write_b16_d16_hi v218, v20
	ds_write_b16_d16_hi v218, v21 offset:144
	ds_write_b16_d16_hi v218, v22 offset:288
	ds_write_b16_d16_hi v218, v23 offset:432
	s_cbranch_vccnz .LBB0_1618
	s_waitcnt lgkmcnt(6)
	v_mfma_scale_f32_32x32x64_f8f6f4 v[230:245], v[32:39], v[246:253], 0, v208, v208 op_sel_hi:[0,0,0]
	v_cvt_pk_bf16_f32 v16, v136, v137
	v_cvt_pk_bf16_f32 v17, v138, v139
	ds_write_b64 v201, v[16:17] offset:0
	v_cvt_pk_bf16_f32 v18, v148, v149
	v_cvt_pk_bf16_f32 v19, v150, v151
	ds_write_b64 v201, v[18:19] offset:4736
	v_cvt_pk_bf16_f32 v20, v160, v161
	v_cvt_pk_bf16_f32 v21, v162, v163
	ds_write_b64 v201, v[20:21] offset:9472
	v_cvt_pk_bf16_f32 v22, v144, v145
	v_cvt_pk_bf16_f32 v23, v146, v147
	ds_write_b64 v201, v[22:23] offset:14208
	ds_read_b128 v[246:249], v207 offset:128
	ds_read_b128 v[250:253], v207 offset:144
	s_waitcnt lgkmcnt(10)
	v_mfma_scale_f32_32x32x64_f8f6f4 v[230:245], v[40:47], v[24:31], v[230:245], v208, v208 op_sel_hi:[0,0,0]
	v_cvt_pk_bf16_f32 v16, v156, v157
	v_cvt_pk_bf16_f32 v17, v158, v159
	ds_write_b64 v201, v[16:17] offset:18944
	v_cvt_pk_bf16_f32 v18, v140, v141
	v_cvt_pk_bf16_f32 v19, v142, v143
	ds_write_b64 v201, v[18:19] offset:23680
	v_cvt_pk_bf16_f32 v20, v152, v153
	v_cvt_pk_bf16_f32 v21, v154, v155
	ds_write_b64 v201, v[20:21] offset:28416
	v_cvt_pk_bf16_f32 v22, v164, v165
	v_cvt_pk_bf16_f32 v23, v166, v167
	ds_write_b64 v201, v[22:23] offset:33152
	v_mul_f32_e32 v18, v132, v132
	v_fmac_f32_e32 v18, v133, v133
	v_fmac_f32_e32 v18, v134, v134
	v_fmac_f32_e32 v18, v135, v135
	v_cvt_pk_bf16_f32 v16, v132, v133
	v_cvt_pk_bf16_f32 v17, v134, v135
	v_add_f32_dpp v18, v18, v18 quad_perm:[1,0,3,2] row_mask:0xf bank_mask:0xf
	ds_write_b64 v213, v[16:17] offset:512
	s_nop 0
	v_add_f32_dpp v18, v18, v18 quad_perm:[2,3,0,1] row_mask:0xf bank_mask:0xf
	s_nop 1
	v_add_f32_dpp v18, v18, v18 row_half_mirror row_mask:0xf bank_mask:0xf
	v_mul_f32_e32 v18, 0.5, v18
	ds_write_b32 v202, v18
	ds_read_b128 v[24:27], v207 offset:192
	ds_read_b128 v[28:31], v207 offset:208
	s_waitcnt lgkmcnt(8)
	v_mfma_scale_f32_32x32x64_f8f6f4 v[230:245], v[48:55], v[246:253], v[230:245], v208, v208 op_sel_hi:[0,0,0]
	s_add_i32 s2, s41, 1
	v_readlane_b32 s2, v227, s2
	s_ashr_i32 s3, s2, 31
	s_lshl_b64 s[10:11], s[2:3], 17
	v_lshl_add_u64 v[16:17], v[182:183], 0, s[10:11]
	v_add_co_u32_e32 v18, vcc, 0x2000, v16
	s_lshl_b64 s[2:3], s[2:3], 14
	s_nop 0
	v_addc_co_u32_e32 v19, vcc, 0, v17, vcc
	global_load_dwordx4 v[136:139], v[16:17], off nt
	global_load_dwordx4 v[148:151], v[18:19], off nt
	v_add_co_u32_e32 v18, vcc, 0x4000, v16
	s_nop 1
	v_addc_co_u32_e32 v19, vcc, 0, v17, vcc
	v_add_co_u32_e32 v20, vcc, 0x6000, v16
	s_nop 1
	v_addc_co_u32_e32 v21, vcc, 0, v17, vcc
	global_load_dwordx4 v[160:163], v[18:19], off nt
	ds_read_b128 v[246:249], v207
	ds_read_b128 v[250:253], v207 offset:16
	s_waitcnt lgkmcnt(2)
	v_mfma_scale_f32_32x32x64_f8f6f4 v[230:245], v[56:63], v[24:31], v[230:245], v208, v208 op_sel_hi:[0,0,0]
	global_load_dwordx4 v[144:147], v[20:21], off nt
	v_add_co_u32_e32 v18, vcc, 0x8000, v16
	s_nop 1
	v_addc_co_u32_e32 v19, vcc, 0, v17, vcc
	v_add_co_u32_e32 v20, vcc, 0xa000, v16
	s_nop 1
	v_addc_co_u32_e32 v21, vcc, 0, v17, vcc
	global_load_dwordx4 v[156:159], v[18:19], off nt
	global_load_dwordx4 v[140:143], v[20:21], off nt
	v_add_co_u32_e32 v18, vcc, 0xc000, v16
	s_nop 1
	v_addc_co_u32_e32 v19, vcc, 0, v17, vcc
	v_add_co_u32_e32 v16, vcc, 0xe000, v16
	s_nop 1
	v_addc_co_u32_e32 v17, vcc, 0, v17, vcc
	global_load_dwordx4 v[152:155], v[18:19], off nt
	global_load_dwordx4 v[164:167], v[16:17], off nt
	v_lshl_add_u64 v[16:17], v[184:185], 0, s[2:3]
	global_load_dwordx4 v[132:135], v[16:17], off nt
	ds_read_b128 v[24:27], v207 offset:64
	ds_read_b128 v[28:31], v207 offset:80
	v_mul_f32_e32 v180, v231, v231
	v_fmac_f32_e32 v180, v230, v230
	v_fmac_f32_e32 v180, v232, v232
	v_fmac_f32_e32 v180, v233, v233
	v_fmac_f32_e32 v180, v234, v234
	v_fmac_f32_e32 v180, v235, v235
	v_fmac_f32_e32 v180, v236, v236
	v_fmac_f32_e32 v180, v237, v237
	v_fmac_f32_e32 v180, v238, v238
	v_fmac_f32_e32 v180, v239, v239
	v_fmac_f32_e32 v180, v240, v240
	v_fmac_f32_e32 v180, v241, v241
	v_fmac_f32_e32 v180, v242, v242
	v_fmac_f32_e32 v180, v243, v243
	v_fmac_f32_e32 v180, v244, v244
	v_fmac_f32_e32 v180, v245, v245
	s_waitcnt lgkmcnt(2)
	v_mfma_scale_f32_32x32x64_f8f6f4 v[230:245], v[64:71], v[246:253], 0, v208, v208 op_sel_hi:[0,0,0]
	ds_read_b128 v[246:249], v207 offset:128
	ds_read_b128 v[250:253], v207 offset:144
	s_waitcnt lgkmcnt(2)
	v_mfma_scale_f32_32x32x64_f8f6f4 v[230:245], v[72:79], v[24:31], v[230:245], v208, v208 op_sel_hi:[0,0,0]
	ds_read_b128 v[24:27], v207 offset:192
	ds_read_b128 v[28:31], v207 offset:208
	s_waitcnt lgkmcnt(2)
	v_mfma_scale_f32_32x32x64_f8f6f4 v[230:245], v[80:87], v[246:253], v[230:245], v208, v208 op_sel_hi:[0,0,0]
	ds_read_b128 v[246:249], v207 offset:8704
	ds_read_b128 v[250:253], v207 offset:8720
	s_waitcnt lgkmcnt(2)
	v_mfma_scale_f32_32x32x64_f8f6f4 v[230:245], v[88:95], v[24:31], v[230:245], v208, v208 op_sel_hi:[0,0,0]
	ds_read_b128 v[24:27], v207 offset:8768
	ds_read_b128 v[28:31], v207 offset:8784
	s_nop 15
	s_nop 1
	v_fmac_f32_e32 v180, v230, v230
	v_fmac_f32_e32 v180, v231, v231
	v_fmac_f32_e32 v180, v232, v232
	v_fmac_f32_e32 v180, v233, v233
	v_fmac_f32_e32 v180, v234, v234
	v_fmac_f32_e32 v180, v235, v235
	v_fmac_f32_e32 v180, v236, v236
	v_fmac_f32_e32 v180, v237, v237
	v_fmac_f32_e32 v180, v238, v238
	v_fmac_f32_e32 v180, v239, v239
	v_fmac_f32_e32 v180, v240, v240
	v_fmac_f32_e32 v180, v241, v241
	v_fmac_f32_e32 v180, v242, v242
	v_fmac_f32_e32 v180, v243, v243
	v_fmac_f32_e32 v180, v244, v244
	v_fmac_f32_e32 v180, v245, v245
	s_waitcnt lgkmcnt(2)
	v_mfma_scale_f32_32x32x64_f8f6f4 v[230:245], v[32:39], v[246:253], 0, v208, v208 op_sel_hi:[0,0,0]
	ds_read_b128 v[246:249], v207 offset:8832
	ds_read_b128 v[250:253], v207 offset:8848
	s_waitcnt lgkmcnt(2)
	v_mfma_scale_f32_32x32x64_f8f6f4 v[230:245], v[40:47], v[24:31], v[230:245], v208, v208 op_sel_hi:[0,0,0]
	ds_read_b128 v[24:27], v207 offset:8896
	ds_read_b128 v[28:31], v207 offset:8912
	s_waitcnt lgkmcnt(2)
	v_mfma_scale_f32_32x32x64_f8f6f4 v[230:245], v[48:55], v[246:253], v[230:245], v208, v208 op_sel_hi:[0,0,0]
	ds_read_b128 v[246:249], v207 offset:8704
	ds_read_b128 v[250:253], v207 offset:8720
	s_waitcnt lgkmcnt(2)
	v_mfma_scale_f32_32x32x64_f8f6f4 v[230:245], v[56:63], v[24:31], v[230:245], v208, v208 op_sel_hi:[0,0,0]
	ds_read_b128 v[24:27], v207 offset:8768
	ds_read_b128 v[28:31], v207 offset:8784
	s_nop 15
	s_nop 1
	v_mul_f32_e32 v229, v231, v231
	v_fmac_f32_e32 v229, v230, v230
	v_fmac_f32_e32 v229, v232, v232
	v_fmac_f32_e32 v229, v233, v233
	v_fmac_f32_e32 v229, v234, v234
	v_fmac_f32_e32 v229, v235, v235
	v_fmac_f32_e32 v229, v236, v236
	v_fmac_f32_e32 v229, v237, v237
	v_fmac_f32_e32 v229, v238, v238
	v_fmac_f32_e32 v229, v239, v239
	v_fmac_f32_e32 v229, v240, v240
	v_fmac_f32_e32 v229, v241, v241
	v_fmac_f32_e32 v229, v242, v242
	v_fmac_f32_e32 v229, v243, v243
	v_fmac_f32_e32 v229, v244, v244
	v_fmac_f32_e32 v229, v245, v245
	s_waitcnt lgkmcnt(2)
	v_mfma_scale_f32_32x32x64_f8f6f4 v[230:245], v[64:71], v[246:253], 0, v208, v208 op_sel_hi:[0,0,0]
	ds_read_b128 v[246:249], v207 offset:8832
	ds_read_b128 v[250:253], v207 offset:8848
	s_waitcnt lgkmcnt(2)
	v_mfma_scale_f32_32x32x64_f8f6f4 v[230:245], v[72:79], v[24:31], v[230:245], v208, v208 op_sel_hi:[0,0,0]
	ds_read_b128 v[24:27], v207 offset:8896
	ds_read_b128 v[28:31], v207 offset:8912
	s_waitcnt lgkmcnt(2)
	v_mfma_scale_f32_32x32x64_f8f6f4 v[230:245], v[80:87], v[246:253], v[230:245], v208, v208 op_sel_hi:[0,0,0]
	s_waitcnt lgkmcnt(0)
	v_mfma_scale_f32_32x32x64_f8f6f4 v[230:245], v[88:95], v[24:31], v[230:245], v208, v208 op_sel_hi:[0,0,0]
	s_waitcnt vmcnt(9)
	v_cvt_pk_fp8_f32 v16, v96, v97
	v_cvt_pk_fp8_f32 v17, v100, v101
	v_cvt_pk_fp8_f32 v18, v104, v105
	v_cvt_pk_fp8_f32 v19, v108, v109
	v_cvt_pk_fp8_f32 v20, v112, v113
	v_cvt_pk_fp8_f32 v21, v116, v117
	v_cvt_pk_fp8_f32 v22, v120, v121
	v_cvt_pk_fp8_f32 v23, v124, v125
	v_cvt_pk_fp8_f32 v16, v98, v99 op_sel:[0,0,1]
	v_cvt_pk_fp8_f32 v17, v102, v103 op_sel:[0,0,1]
	v_cvt_pk_fp8_f32 v18, v106, v107 op_sel:[0,0,1]
	v_cvt_pk_fp8_f32 v19, v110, v111 op_sel:[0,0,1]
	v_cvt_pk_fp8_f32 v20, v114, v115 op_sel:[0,0,1]
	v_cvt_pk_fp8_f32 v21, v118, v119 op_sel:[0,0,1]
	v_cvt_pk_fp8_f32 v22, v122, v123 op_sel:[0,0,1]
	v_cvt_pk_fp8_f32 v23, v126, v127 op_sel:[0,0,1]
	s_nop 1
	ds_write_b32 v228, v16 offset:17408
	ds_write_b32 v228, v17 offset:19584
	ds_write_b32 v228, v18 offset:21760
	ds_write_b32 v228, v19 offset:23936
	ds_write_b32 v228, v20 offset:26112
	ds_write_b32 v228, v21 offset:28288
	ds_write_b32 v228, v22 offset:30464
	ds_write_b32 v228, v23 offset:32640
	v_fmac_f32_e32 v229, v230, v230
	v_fmac_f32_e32 v229, v231, v231
	v_fmac_f32_e32 v229, v232, v232
	v_fmac_f32_e32 v229, v233, v233
	v_fmac_f32_e32 v229, v234, v234
	v_fmac_f32_e32 v229, v235, v235
	v_fmac_f32_e32 v229, v236, v236
	v_fmac_f32_e32 v229, v237, v237
	v_fmac_f32_e32 v229, v238, v238
	v_fmac_f32_e32 v229, v239, v239
	v_fmac_f32_e32 v229, v240, v240
	v_fmac_f32_e32 v229, v241, v241
	v_fmac_f32_e32 v229, v242, v242
	v_fmac_f32_e32 v229, v243, v243
	v_fmac_f32_e32 v229, v244, v244
	v_fmac_f32_e32 v229, v245, v245
